# z7 + attention QK^T: five K-fragment ds_reads in flight instead of one (spare VGPRs v216-223, v242-245)
# speedup vs baseline: 1.0032x; 1.0032x over previous
.LBB0_302:
	v_lshl_add_u64 v[70:71], v[150:151], 0, v[146:147]
	v_add_co_u32_e32 v66, vcc, 0x4da00000, v70
	v_lshl_add_u64 v[82:83], v[148:149], 0, v[146:147]
	s_nop 0
	v_addc_co_u32_e32 v67, vcc, 0, v71, vcc
	v_add_co_u32_e32 v70, vcc, 0x51a00000, v70
	global_load_dwordx4 v[66:69], v[66:67], off
	s_nop 0
	v_addc_co_u32_e32 v71, vcc, 0, v71, vcc
	v_add_co_u32_e32 v74, vcc, 0x4da04000, v82
	global_load_dwordx4 v[70:73], v[70:71], off
	s_nop 0
	v_addc_co_u32_e32 v75, vcc, 0, v83, vcc
	v_add_co_u32_e32 v78, vcc, 0x51a04000, v82
	global_load_dwordx4 v[74:77], v[74:75], off
	s_nop 0
	v_addc_co_u32_e32 v79, vcc, 0, v83, vcc
	v_add_co_u32_e32 v166, vcc, 0x4da08000, v82
	global_load_dwordx4 v[78:81], v[78:79], off
	s_nop 0
	v_addc_co_u32_e32 v167, vcc, 0, v83, vcc
	v_add_co_u32_e32 v170, vcc, 0x51a08000, v82
	global_load_dwordx4 v[166:169], v[166:167], off
	s_nop 0
	v_addc_co_u32_e32 v171, vcc, 0, v83, vcc
	v_add_co_u32_e32 v174, vcc, 0x4da0c000, v82
	global_load_dwordx4 v[170:173], v[170:171], off
	s_nop 0
	v_addc_co_u32_e32 v175, vcc, 0, v83, vcc
	v_add_co_u32_e32 v178, vcc, 0x51a0c000, v82
	global_load_dwordx4 v[174:177], v[174:175], off
	s_nop 0
	v_addc_co_u32_e32 v179, vcc, 0, v83, vcc
	v_add_co_u32_e32 v182, vcc, 0x4da10000, v82
	global_load_dwordx4 v[178:181], v[178:179], off
	s_nop 0
	v_addc_co_u32_e32 v183, vcc, 0, v83, vcc
	v_add_co_u32_e32 v188, vcc, 0x51a10000, v82
	global_load_dwordx4 v[182:185], v[182:183], off
	s_nop 0
	v_addc_co_u32_e32 v189, vcc, 0, v83, vcc
	v_add_co_u32_e32 v192, vcc, 0x4da14000, v82
	global_load_dwordx4 v[188:191], v[188:189], off
	s_nop 0
	v_addc_co_u32_e32 v193, vcc, 0, v83, vcc
	v_add_co_u32_e32 v196, vcc, 0x51a14000, v82
	global_load_dwordx4 v[192:195], v[192:193], off
	s_nop 0
	v_addc_co_u32_e32 v197, vcc, 0, v83, vcc
	v_add_co_u32_e32 v200, vcc, 0x4da18000, v82
	global_load_dwordx4 v[196:199], v[196:197], off
	s_nop 0
	v_addc_co_u32_e32 v201, vcc, 0, v83, vcc
	v_add_co_u32_e32 v204, vcc, 0x51a18000, v82
	global_load_dwordx4 v[200:203], v[200:201], off
	s_nop 0
	v_addc_co_u32_e32 v205, vcc, 0, v83, vcc
	v_add_co_u32_e32 v208, vcc, 0x4da1c000, v82
	global_load_dwordx4 v[204:207], v[204:205], off
	s_nop 0
	v_addc_co_u32_e32 v209, vcc, 0, v83, vcc
	v_add_co_u32_e32 v82, vcc, 0x51a1c000, v82
	global_load_dwordx4 v[208:211], v[208:209], off
	s_nop 0
	v_addc_co_u32_e32 v83, vcc, 0, v83, vcc
	global_load_dwordx4 v[212:215], v[82:83], off
	s_waitcnt lgkmcnt(0)
	v_lshl_add_u64 v[148:149], v[148:149], 0, s[92:93]
	v_lshl_add_u64 v[150:151], v[150:151], 0, s[92:93]
	s_waitcnt vmcnt(15)
	ds_write_b128 v162, v[66:69]
	s_waitcnt vmcnt(14)
	ds_write_b128 v162, v[70:73] offset:8704
	s_waitcnt vmcnt(13)
	ds_write_b128 v162, v[74:77] offset:1088
	s_waitcnt vmcnt(12)
	ds_write_b128 v162, v[78:81] offset:9792
	s_waitcnt vmcnt(11)
	ds_write_b128 v162, v[166:169] offset:2176
	s_waitcnt vmcnt(10)
	ds_write_b128 v162, v[170:173] offset:10880
	s_waitcnt vmcnt(9)
	ds_write_b128 v162, v[174:177] offset:3264
	s_waitcnt vmcnt(8)
	ds_write_b128 v162, v[178:181] offset:11968
	s_waitcnt vmcnt(7)
	ds_write_b128 v162, v[182:185] offset:4352
	s_waitcnt vmcnt(6)
	ds_write_b128 v162, v[188:191] offset:13056
	s_waitcnt vmcnt(5)
	ds_write_b128 v162, v[192:195] offset:5440
	s_waitcnt vmcnt(4)
	ds_write_b128 v162, v[196:199] offset:14144
	s_waitcnt vmcnt(3)
	ds_write_b128 v162, v[200:203] offset:6528
	s_waitcnt vmcnt(2)
	ds_write_b128 v162, v[204:207] offset:15232
	s_waitcnt vmcnt(1)
	ds_write_b128 v162, v[208:211] offset:7616
	s_waitcnt vmcnt(0)
	ds_write_b128 v162, v[212:215] offset:16320
	s_waitcnt lgkmcnt(0)
	ds_read_b128 v[66:69], v163
	ds_read_b128 v[166:169], v163 offset:32
	ds_read_b128 v[216:219], v163 offset:64
	ds_read_b128 v[220:223], v163 offset:96
	ds_read_b128 v[242:245], v163 offset:128
	s_waitcnt lgkmcnt(4)
	v_mfma_f32_32x32x16_bf16 v[66:81], v[66:69], v[92:95], 0
	s_waitcnt lgkmcnt(3)
	v_mfma_f32_32x32x16_bf16 v[66:81], v[166:169], v[96:99], v[66:81]
	ds_read_b128 v[166:169], v163 offset:160
	s_waitcnt lgkmcnt(3)
	v_mfma_f32_32x32x16_bf16 v[66:81], v[216:219], v[100:103], v[66:81]
	ds_read_b128 v[216:219], v163 offset:192
	s_waitcnt lgkmcnt(3)
	v_mfma_f32_32x32x16_bf16 v[66:81], v[220:223], v[104:107], v[66:81]
	ds_read_b128 v[220:223], v163 offset:224
	s_waitcnt lgkmcnt(3)
	v_mfma_f32_32x32x16_bf16 v[66:81], v[242:245], v[108:111], v[66:81]
	s_waitcnt lgkmcnt(2)
	v_mfma_f32_32x32x16_bf16 v[66:81], v[166:169], v[112:115], v[66:81]
	s_waitcnt lgkmcnt(1)
	v_mfma_f32_32x32x16_bf16 v[66:81], v[216:219], v[120:123], v[66:81]
	s_waitcnt lgkmcnt(0)
	v_mfma_f32_32x32x16_bf16 v[66:81], v[220:223], v[116:119], v[66:81]
	s_nop 11
	v_exp_f32_e64 v1, -|v66|
	v_max_f32_e32 v165, v69, v69
	v_min_f32_e32 v165, 0, v165
	v_add_f32_e32 v1, 1.0, v1
	v_log_f32_e32 v170, v1
	v_max_f32_e64 v1, -v66, -v66
	v_min_f32_e32 v82, 0, v1
	v_exp_f32_e64 v1, -|v67|
	v_max_f32_e32 v66, v66, v66
	v_min_f32_e32 v66, 0, v66
	v_sub_f32_e32 v66, v66, v170
	v_add_f32_e32 v1, 1.0, v1
	v_log_f32_e32 v171, v1
	v_max_f32_e32 v1, v67, v67
	v_max_f32_e64 v67, -v67, -v67
	v_min_f32_e32 v83, 0, v67
	v_pk_add_f32 v[172:173], v[82:83], v[170:171] neg_lo:[0,1] neg_hi:[0,1]
	v_exp_f32_e64 v67, -|v68|
	v_exp_f32_e64 v83, -|v69|
	v_max_f32_e64 v69, -v69, -v69
	v_min_f32_e32 v69, 0, v69
	v_add_f32_e32 v67, 1.0, v67
	v_add_f32_e32 v83, 1.0, v83
	v_log_f32_e32 v82, v67
	v_log_f32_e32 v83, v83
	v_max_f32_e32 v67, v68, v68
	v_max_f32_e64 v68, -v68, -v68
	v_min_f32_e32 v68, 0, v68
	v_pk_add_f32 v[174:175], v[68:69], v[82:83] neg_lo:[0,1] neg_hi:[0,1]
	v_exp_f32_e64 v68, -|v70|
	v_sub_f32_e32 v165, v165, v83
	v_min_f32_e32 v67, 0, v67
	v_sub_f32_e32 v67, v67, v82
	v_add_f32_e32 v68, 1.0, v68
	v_log_f32_e32 v69, v68
	v_max_f32_e32 v68, v70, v70
	v_min_f32_e32 v166, 0, v68
	v_max_f32_e64 v68, -v70, -v70
	v_min_f32_e32 v83, 0, v68
	v_exp_f32_e64 v68, -|v71|
	v_max_f32_e32 v70, v71, v71
	v_max_f32_e64 v71, -v71, -v71
	v_min_f32_e32 v70, 0, v70
	v_add_f32_e32 v68, 1.0, v68
	v_log_f32_e32 v68, v68
	v_min_f32_e32 v82, 0, v71
	v_min_f32_e32 v1, 0, v1
	v_sub_f32_e32 v1, v1, v171
	v_sub_f32_e32 v192, v70, v68
	v_pk_add_f32 v[176:177], v[82:83], v[68:69] neg_lo:[0,1] neg_hi:[0,1]
	v_exp_f32_e64 v68, -|v72|
	v_sub_f32_e32 v171, v166, v69
	v_max_f32_e32 v70, v73, v73
	v_add_f32_e32 v68, 1.0, v68
	v_log_f32_e32 v69, v68
	v_max_f32_e32 v68, v72, v72
	v_min_f32_e32 v82, 0, v68
	v_max_f32_e64 v68, -v72, -v72
	v_min_f32_e32 v71, 0, v68
	v_exp_f32_e64 v68, -|v73|
	v_min_f32_e32 v72, 0, v70
	v_max_f32_e64 v70, -v73, -v73
	v_min_f32_e32 v70, 0, v70
	v_add_f32_e32 v68, 1.0, v68
	v_log_f32_e32 v68, v68
	v_sub_f32_e32 v193, v82, v69
	v_sub_f32_e32 v194, v72, v68
	v_pk_add_f32 v[178:179], v[70:71], v[68:69] neg_lo:[0,1] neg_hi:[0,1]
	v_exp_f32_e64 v68, -|v74|
	v_max_f32_e32 v70, v75, v75
	v_min_f32_e32 v73, 0, v70
	v_max_f32_e64 v70, -v75, -v75
	v_add_f32_e32 v68, 1.0, v68
	v_log_f32_e32 v69, v68
	v_max_f32_e32 v68, v74, v74
	v_min_f32_e32 v72, 0, v68
	v_max_f32_e64 v68, -v74, -v74
	v_min_f32_e32 v71, 0, v68
	v_exp_f32_e64 v68, -|v75|
	v_min_f32_e32 v70, 0, v70
	v_sub_f32_e32 v195, v72, v69
	v_add_f32_e32 v68, 1.0, v68
	v_log_f32_e32 v68, v68
	s_nop 0
	v_sub_f32_e32 v196, v73, v68
	v_pk_add_f32 v[180:181], v[70:71], v[68:69] neg_lo:[0,1] neg_hi:[0,1]
	v_exp_f32_e64 v68, -|v76|
	v_max_f32_e32 v70, v77, v77
	v_min_f32_e32 v73, 0, v70
	v_max_f32_e64 v70, -v77, -v77
	v_add_f32_e32 v68, 1.0, v68
	v_log_f32_e32 v69, v68
	v_max_f32_e32 v68, v76, v76
	v_min_f32_e32 v72, 0, v68
	v_max_f32_e64 v68, -v76, -v76
	v_min_f32_e32 v71, 0, v68
	v_exp_f32_e64 v68, -|v77|
	v_min_f32_e32 v70, 0, v70
	v_sub_f32_e32 v197, v72, v69
	v_pk_mov_b32 v[166:167], v[180:181], v[180:181] op_sel:[1,0]
	v_add_f32_e32 v68, 1.0, v68
	v_log_f32_e32 v68, v68
	v_cvt_pk_bf16_f32 v166, v166, v167
	v_sub_f32_e32 v198, v73, v68
	v_pk_add_f32 v[182:183], v[70:71], v[68:69] neg_lo:[0,1] neg_hi:[0,1]
	v_exp_f32_e64 v68, -|v78|
	v_max_f32_e32 v70, v79, v79
	v_min_f32_e32 v73, 0, v70
	v_max_f32_e64 v70, -v79, -v79
	v_add_f32_e32 v68, 1.0, v68
	v_log_f32_e32 v69, v68
	v_max_f32_e32 v68, v78, v78
	v_min_f32_e32 v72, 0, v68
	v_max_f32_e64 v68, -v78, -v78
	v_min_f32_e32 v71, 0, v68
	v_exp_f32_e64 v68, -|v79|
	v_min_f32_e32 v70, 0, v70
	v_sub_f32_e32 v199, v72, v69
	v_pk_mov_b32 v[168:169], v[182:183], v[182:183] op_sel:[1,0]
	v_add_f32_e32 v68, 1.0, v68
	v_log_f32_e32 v68, v68
	v_cvt_pk_bf16_f32 v167, v168, v169
	v_sub_f32_e32 v200, v73, v68
	v_pk_add_f32 v[184:185], v[70:71], v[68:69] neg_lo:[0,1] neg_hi:[0,1]
	v_exp_f32_e64 v68, -|v80|
	v_max_f32_e32 v70, v81, v81
	v_min_f32_e32 v73, 0, v70
	v_max_f32_e64 v70, -v81, -v81
	v_add_f32_e32 v68, 1.0, v68
	v_log_f32_e32 v69, v68
	v_max_f32_e32 v68, v80, v80
	v_min_f32_e32 v72, 0, v68
	v_max_f32_e64 v68, -v80, -v80
	v_min_f32_e32 v71, 0, v68
	v_exp_f32_e64 v68, -|v81|
	v_min_f32_e32 v70, 0, v70
	v_sub_f32_e32 v201, v72, v69
	v_pk_mov_b32 v[168:169], v[184:185], v[184:185] op_sel:[1,0]
	v_add_f32_e32 v68, 1.0, v68
	v_log_f32_e32 v68, v68
	v_cvt_pk_bf16_f32 v168, v168, v169
	v_sub_f32_e32 v202, v73, v68
	v_pk_add_f32 v[188:189], v[70:71], v[68:69] neg_lo:[0,1] neg_hi:[0,1]
	v_pk_mov_b32 v[70:71], v[176:177], v[176:177] op_sel:[1,0]
	v_pk_mov_b32 v[72:73], v[178:179], v[178:179] op_sel:[1,0]
	v_cvt_pk_bf16_f32 v68, v172, v173
	v_cvt_pk_bf16_f32 v69, v174, v175
	v_cvt_pk_bf16_f32 v70, v70, v71
	v_cvt_pk_bf16_f32 v71, v72, v73
	v_pk_mov_b32 v[190:191], v[188:189], v[188:189] op_sel:[1,0]
	s_nop 0
	v_mfma_f32_32x32x16_bf16 v[68:83], v[84:87], v[68:71], 0
	v_cvt_pk_bf16_f32 v169, v190, v191
	s_nop 1
	v_mfma_f32_32x32x16_bf16 v[68:83], v[88:91], v[166:169], v[68:83]
	v_add_f32_e32 v166, 0, v172
	v_add_f32_e32 v166, v173, v166
	v_add_f32_e32 v166, v174, v166
	v_add_f32_e32 v166, v175, v166
	v_add_f32_e32 v166, v177, v166
	v_add_f32_e32 v166, v176, v166
	v_add_f32_e32 v166, v179, v166
	s_nop 4
	v_add_f32_e32 v67, v70, v67
	v_add_f32_e32 v70, v73, v192
	v_add_f32_e32 v73, v76, v195
	v_add_f32_e32 v73, v164, v73
	v_add_f32_e32 v66, v68, v66
	v_add_f32_e32 v68, v71, v165
	v_exp_f32_e32 v165, v73
	v_add_f32_e32 v73, v77, v196
	v_add_f32_e32 v73, v164, v73
	v_exp_f32_e32 v170, v73
	v_add_f32_e32 v73, v78, v197
	v_add_f32_e32 v73, v164, v73
	v_add_f32_e32 v1, v69, v1
	v_add_f32_e32 v69, v72, v171
	v_exp_f32_e32 v171, v73
	v_add_f32_e32 v73, v79, v198
	v_add_f32_e32 v73, v164, v73
	v_add_f32_e32 v166, v178, v166
	v_exp_f32_e32 v172, v73
	v_add_f32_e32 v73, v80, v199
	v_add_f32_e32 v166, v181, v166
	v_add_f32_e32 v73, v164, v73
	v_add_f32_e32 v166, v180, v166
	v_exp_f32_e32 v173, v73
	v_add_f32_e32 v73, v81, v200
	v_add_f32_e32 v166, v183, v166
	v_add_f32_e32 v73, v164, v73
	v_add_f32_e32 v166, v182, v166
	v_exp_f32_e32 v174, v73
	v_add_f32_e32 v73, v82, v201
	v_add_f32_e32 v166, v185, v166
	v_add_f32_e32 v73, v164, v73
	v_add_f32_e32 v166, v184, v166
	v_exp_f32_e32 v82, v73
	v_add_f32_e32 v73, v83, v202
	v_add_f32_e32 v166, v189, v166
	v_add_f32_e32 v73, v164, v73
	v_add_f32_e32 v71, v74, v193
	v_add_f32_e32 v72, v75, v194
	v_exp_f32_e32 v83, v73
	v_add_f32_e32 v73, v188, v166
	v_add_f32_e32 v66, v164, v66
	v_add_f32_e32 v1, v164, v1
	v_add_f32_e32 v67, v164, v67
	v_add_f32_e32 v68, v164, v68
	v_add_f32_e32 v69, v164, v69
	v_add_f32_e32 v70, v164, v70
	v_add_f32_e32 v71, v164, v71
	v_add_f32_e32 v72, v164, v72
	ds_bpermute_b32 v74, v145, v73
	v_exp_f32_e32 v66, v66
	v_exp_f32_e32 v1, v1
	v_exp_f32_e32 v67, v67
	v_exp_f32_e32 v68, v68
	v_exp_f32_e32 v69, v69
	v_exp_f32_e32 v70, v70
	v_exp_f32_e32 v71, v71
	v_exp_f32_e32 v72, v72
	s_waitcnt lgkmcnt(0)
	v_add_f32_e32 v175, v73, v74
	v_cvt_pk_bf16_f32 v66, v66, v1
	v_cvt_pk_bf16_f32 v67, v67, v68
	v_cvt_pk_bf16_f32 v68, v69, v70
	v_cvt_pk_bf16_f32 v69, v71, v72
	ds_read_b64_tr_b16 v[74:75], v131
	ds_read_b64_tr_b16 v[76:77], v133
	ds_read_b64_tr_b16 v[70:71], v135
	ds_read_b64_tr_b16 v[72:73], v137
	s_waitcnt lgkmcnt(0)
	ds_read_b64_tr_b16 v[166:167], v139
	ds_read_b64_tr_b16 v[168:169], v141
	ds_read_b64_tr_b16 v[78:79], v152
	ds_read_b64_tr_b16 v[80:81], v153
	s_waitcnt lgkmcnt(0)
	v_add_f32_e32 v164, v164, v175
	v_cmp_gt_f32_e32 vcc, s73, v164
	v_mfma_f32_32x32x16_bf16 v[50:65], v[74:77], v[66:69], v[50:65]
	s_cmp_lg_u64 vcc, exec
	s_cselect_b64 s[12:13], -1, 0
	s_cmp_lg_u32 s10, 0
	s_cselect_b64 s[14:15], -1, 0
	s_and_b64 vcc, s[14:15], s[12:13]
	s_add_i32 s10, s10, 1
	s_and_b64 vcc, exec, vcc
	v_mfma_f32_32x32x16_bf16 v[34:49], v[70:73], v[66:69], v[34:49]
	ds_read_b64_tr_b16 v[74:75], v154
	ds_read_b64_tr_b16 v[76:77], v155
	ds_read_b64_tr_b16 v[70:71], v156
	ds_read_b64_tr_b16 v[72:73], v157
	s_waitcnt lgkmcnt(0)
	v_mfma_f32_32x32x16_bf16 v[18:33], v[166:169], v[66:69], v[18:33]
	v_mfma_f32_32x32x16_bf16 v[2:17], v[78:81], v[66:69], v[2:17]
	v_cvt_pk_bf16_f32 v66, v165, v170
	v_cvt_pk_bf16_f32 v67, v171, v172
	v_cvt_pk_bf16_f32 v68, v173, v174
	v_cvt_pk_bf16_f32 v69, v82, v83
	ds_read_b64_tr_b16 v[166:167], v158
	ds_read_b64_tr_b16 v[168:169], v159
	ds_read_b64_tr_b16 v[78:79], v160
	ds_read_b64_tr_b16 v[80:81], v161
	s_waitcnt lgkmcnt(0)
	s_nop 1
	v_mfma_f32_32x32x16_bf16 v[50:65], v[74:77], v[66:69], v[50:65]
	v_mfma_f32_32x32x16_bf16 v[34:49], v[70:73], v[66:69], v[34:49]
	v_mfma_f32_32x32x16_bf16 v[18:33], v[166:169], v[66:69], v[18:33]
	v_mfma_f32_32x32x16_bf16 v[2:17], v[78:81], v[66:69], v[2:17]
	s_cbranch_vccnz .LBB0_302
	s_branch .LBB0_299
